# attention main loops: saddr K/V prefetch addressing, straightened softmax-check control flow (rescale out of line), folded canonical max pairs
# speedup vs baseline: 1.0111x; 1.0111x over previous
.Lat1_first:
	s_mov_b64 s[10:11], -1
	v_mov_b32_e32 v84, v83
	s_branch .Lat1_apply
.Lat1_resc:
	s_mov_b64 s[10:11], 0
	v_max_f32_e32 v84, 0, v83
.Lat1_apply:
	v_add_f32_e32 v34, v82, v84
	v_pk_add_f32 v[50:51], v[50:51], v[34:35] op_sel_hi:[1,0] neg_lo:[0,1] neg_hi:[0,1]
	v_pk_add_f32 v[66:67], v[66:67], v[34:35] op_sel_hi:[1,0] neg_lo:[0,1] neg_hi:[0,1]
	v_pk_add_f32 v[52:53], v[52:53], v[34:35] op_sel_hi:[1,0] neg_lo:[0,1] neg_hi:[0,1]
	v_pk_add_f32 v[68:69], v[68:69], v[34:35] op_sel_hi:[1,0] neg_lo:[0,1] neg_hi:[0,1]
	v_pk_add_f32 v[54:55], v[54:55], v[34:35] op_sel_hi:[1,0] neg_lo:[0,1] neg_hi:[0,1]
	v_pk_add_f32 v[70:71], v[70:71], v[34:35] op_sel_hi:[1,0] neg_lo:[0,1] neg_hi:[0,1]
	v_pk_add_f32 v[56:57], v[56:57], v[34:35] op_sel_hi:[1,0] neg_lo:[0,1] neg_hi:[0,1]
	v_pk_add_f32 v[72:73], v[72:73], v[34:35] op_sel_hi:[1,0] neg_lo:[0,1] neg_hi:[0,1]
	v_pk_add_f32 v[58:59], v[58:59], v[34:35] op_sel_hi:[1,0] neg_lo:[0,1] neg_hi:[0,1]
	v_pk_add_f32 v[74:75], v[74:75], v[34:35] op_sel_hi:[1,0] neg_lo:[0,1] neg_hi:[0,1]
	v_pk_add_f32 v[60:61], v[60:61], v[34:35] op_sel_hi:[1,0] neg_lo:[0,1] neg_hi:[0,1]
	v_pk_add_f32 v[76:77], v[76:77], v[34:35] op_sel_hi:[1,0] neg_lo:[0,1] neg_hi:[0,1]
	v_pk_add_f32 v[62:63], v[62:63], v[34:35] op_sel_hi:[1,0] neg_lo:[0,1] neg_hi:[0,1]
	v_pk_add_f32 v[78:79], v[78:79], v[34:35] op_sel_hi:[1,0] neg_lo:[0,1] neg_hi:[0,1]
	v_exp_f32_e64 v35, -v84
	v_add_f32_e32 v204, v205, v84
	v_pk_add_f32 v[64:65], v[64:65], v[34:35] op_sel_hi:[1,0] neg_lo:[0,1] neg_hi:[0,1]
	v_pk_add_f32 v[80:81], v[80:81], v[34:35] op_sel_hi:[1,0] neg_lo:[0,1] neg_hi:[0,1]
	v_cndmask_b32_e64 v36, v35, 1.0, s[10:11]
	v_xor_b32_e32 v34, 0x80000000, v204
	v_pk_mul_f32 v[16:17], v[16:17], v[36:37] op_sel_hi:[1,0]
	v_pk_mul_f32 v[14:15], v[14:15], v[36:37] op_sel_hi:[1,0]
	v_pk_mul_f32 v[12:13], v[12:13], v[36:37] op_sel_hi:[1,0]
	v_pk_mul_f32 v[10:11], v[10:11], v[36:37] op_sel_hi:[1,0]
	v_pk_mul_f32 v[8:9], v[8:9], v[36:37] op_sel_hi:[1,0]
	v_pk_mul_f32 v[6:7], v[6:7], v[36:37] op_sel_hi:[1,0]
	v_pk_mul_f32 v[4:5], v[4:5], v[36:37] op_sel_hi:[1,0]
	v_pk_mul_f32 v[2:3], v[2:3], v[36:37] op_sel_hi:[1,0]
	v_pk_mul_f32 v[32:33], v[32:33], v[36:37] op_sel_hi:[1,0]
	v_pk_mul_f32 v[30:31], v[30:31], v[36:37] op_sel_hi:[1,0]
	v_pk_mul_f32 v[28:29], v[28:29], v[36:37] op_sel_hi:[1,0]
	v_pk_mul_f32 v[26:27], v[26:27], v[36:37] op_sel_hi:[1,0]
	v_pk_mul_f32 v[24:25], v[24:25], v[36:37] op_sel_hi:[1,0]
	v_pk_mul_f32 v[22:23], v[22:23], v[36:37] op_sel_hi:[1,0]
	v_pk_mul_f32 v[20:21], v[20:21], v[36:37] op_sel_hi:[1,0]
	v_pk_mul_f32 v[18:19], v[18:19], v[36:37] op_sel_hi:[1,0]
	v_mul_f32_e32 v203, v203, v36
	v_mov_b32_e32 v35, v34
	v_mov_b32_e32 v36, v34
	v_mov_b32_e32 v37, v34
	v_mov_b32_e32 v38, v34
	v_mov_b32_e32 v39, v34
	v_mov_b32_e32 v40, v34
	v_mov_b32_e32 v41, v34
	v_mov_b32_e32 v42, v34
	v_mov_b32_e32 v43, v34
	v_mov_b32_e32 v44, v34
	v_mov_b32_e32 v45, v34
	v_mov_b32_e32 v46, v34
	v_mov_b32_e32 v47, v34
	v_mov_b32_e32 v48, v34
	v_mov_b32_e32 v49, v34
	s_branch .LBB0_813
.Lat1_resc_b:
	v_max_f32_e32 v34, v51, v51
	v_max_f32_e32 v35, 0, v34
	v_exp_f32_e64 v36, -v35
	v_add_f32_e32 v34, v50, v35
	v_add_f32_e32 v205, v204, v35
	v_pk_add_f32 v[82:83], v[82:83], v[34:35] op_sel_hi:[1,0] neg_lo:[0,1] neg_hi:[0,1]
	v_pk_add_f32 v[98:99], v[98:99], v[34:35] op_sel_hi:[1,0] neg_lo:[0,1] neg_hi:[0,1]
	v_pk_add_f32 v[84:85], v[84:85], v[34:35] op_sel_hi:[1,0] neg_lo:[0,1] neg_hi:[0,1]
	v_pk_add_f32 v[100:101], v[100:101], v[34:35] op_sel_hi:[1,0] neg_lo:[0,1] neg_hi:[0,1]
	v_pk_add_f32 v[86:87], v[86:87], v[34:35] op_sel_hi:[1,0] neg_lo:[0,1] neg_hi:[0,1]
	v_pk_add_f32 v[102:103], v[102:103], v[34:35] op_sel_hi:[1,0] neg_lo:[0,1] neg_hi:[0,1]
	v_pk_add_f32 v[88:89], v[88:89], v[34:35] op_sel_hi:[1,0] neg_lo:[0,1] neg_hi:[0,1]
	v_pk_add_f32 v[104:105], v[104:105], v[34:35] op_sel_hi:[1,0] neg_lo:[0,1] neg_hi:[0,1]
	v_pk_add_f32 v[90:91], v[90:91], v[34:35] op_sel_hi:[1,0] neg_lo:[0,1] neg_hi:[0,1]
	v_pk_add_f32 v[106:107], v[106:107], v[34:35] op_sel_hi:[1,0] neg_lo:[0,1] neg_hi:[0,1]
	v_pk_add_f32 v[92:93], v[92:93], v[34:35] op_sel_hi:[1,0] neg_lo:[0,1] neg_hi:[0,1]
	v_pk_add_f32 v[108:109], v[108:109], v[34:35] op_sel_hi:[1,0] neg_lo:[0,1] neg_hi:[0,1]
	v_pk_add_f32 v[94:95], v[94:95], v[34:35] op_sel_hi:[1,0] neg_lo:[0,1] neg_hi:[0,1]
	v_pk_add_f32 v[110:111], v[110:111], v[34:35] op_sel_hi:[1,0] neg_lo:[0,1] neg_hi:[0,1]
	v_pk_add_f32 v[96:97], v[96:97], v[34:35] op_sel_hi:[1,0] neg_lo:[0,1] neg_hi:[0,1]
	v_pk_add_f32 v[112:113], v[112:113], v[34:35] op_sel_hi:[1,0] neg_lo:[0,1] neg_hi:[0,1]
	v_xor_b32_e32 v34, 0x80000000, v205
	v_pk_mul_f32 v[16:17], v[16:17], v[36:37] op_sel_hi:[1,0]
	v_pk_mul_f32 v[14:15], v[14:15], v[36:37] op_sel_hi:[1,0]
	v_pk_mul_f32 v[12:13], v[12:13], v[36:37] op_sel_hi:[1,0]
	v_pk_mul_f32 v[10:11], v[10:11], v[36:37] op_sel_hi:[1,0]
	v_pk_mul_f32 v[8:9], v[8:9], v[36:37] op_sel_hi:[1,0]
	v_pk_mul_f32 v[6:7], v[6:7], v[36:37] op_sel_hi:[1,0]
	v_pk_mul_f32 v[4:5], v[4:5], v[36:37] op_sel_hi:[1,0]
	v_pk_mul_f32 v[2:3], v[2:3], v[36:37] op_sel_hi:[1,0]
	v_pk_mul_f32 v[32:33], v[32:33], v[36:37] op_sel_hi:[1,0]
	v_pk_mul_f32 v[30:31], v[30:31], v[36:37] op_sel_hi:[1,0]
	v_pk_mul_f32 v[28:29], v[28:29], v[36:37] op_sel_hi:[1,0]
	v_pk_mul_f32 v[26:27], v[26:27], v[36:37] op_sel_hi:[1,0]
	v_pk_mul_f32 v[24:25], v[24:25], v[36:37] op_sel_hi:[1,0]
	v_pk_mul_f32 v[22:23], v[22:23], v[36:37] op_sel_hi:[1,0]
	v_pk_mul_f32 v[20:21], v[20:21], v[36:37] op_sel_hi:[1,0]
	v_pk_mul_f32 v[18:19], v[18:19], v[36:37] op_sel_hi:[1,0]
	v_mul_f32_e32 v180, v180, v36
	v_mov_b32_e32 v35, v34
	v_mov_b32_e32 v36, v34
	v_mov_b32_e32 v37, v34
	v_mov_b32_e32 v38, v34
	v_mov_b32_e32 v39, v34
	v_mov_b32_e32 v40, v34
	v_mov_b32_e32 v41, v34
	v_mov_b32_e32 v42, v34
	v_mov_b32_e32 v43, v34
	v_mov_b32_e32 v44, v34
	v_mov_b32_e32 v45, v34
	v_mov_b32_e32 v46, v34
	v_mov_b32_e32 v47, v34
	v_mov_b32_e32 v48, v34
	v_mov_b32_e32 v49, v34
	s_branch .LBB0_820

.LBB0_804:
	s_or_b64 exec, exec, s[8:9]
	global_load_dwordx4 v[146:149], v160, s[56:57] offset:128
	v_max_f32_e32 v83, v50, v51
	v_max3_f32 v84, v52, v53, v67
	v_max3_f32 v83, v83, v66, v68
	v_max3_f32 v83, v83, v69, v54
	v_max3_f32 v84, v84, v56, v57
	v_max3_f32 v83, v83, v55, v70
	v_max3_f32 v84, v84, v72, v73
	v_max3_f32 v83, v83, v71, v58
	v_max3_f32 v84, v84, v60, v61
	v_max3_f32 v83, v83, v59, v74
	v_max3_f32 v84, v84, v76, v77
	v_max3_f32 v83, v83, v75, v62
	v_max3_f32 v84, v84, v64, v65
	v_max3_f32 v83, v83, v63, v78
	v_max3_f32 v84, v84, v80, v81
	v_max3_f32 v83, v83, v79, v84
	v_sub_f32_e32 v82, v205, v205
	v_mov_b32_e32 v84, v83
	s_cmp_eq_u32 s12, 0
	s_nop 0
	v_permlane32_swap_b32_e32 v83, v84
	v_max_f32_e32 v83, v83, v84
	v_sub_f32_e32 v83, v83, v82
	s_cbranch_scc1 .Lat1_first
	v_cmp_lt_f32_e32 vcc, s97, v83
	v_cmp_neq_f32_e64 s[8:9], 0, v82
	s_or_b64 vcc, s[8:9], vcc
	s_cbranch_vccnz .Lat1_resc
	v_mov_b32_e32 v204, v205

.LBB0_817:
	s_or_b64 exec, exec, s[8:9]
	global_load_dwordx4 v[146:149], v160, s[56:57] offset:256
	v_add_f32_e32 v50, v66, v50
	v_add_u32_e32 v150, 0x6000, v150
	v_add_u32_e32 v152, 0x6000, v152
	v_add_u32_e32 v160, 0x100, v160
	v_add_f32_e32 v51, v67, v51
	v_add_f32_e32 v52, v68, v52
	v_add_f32_e32 v50, v51, v50
	v_add_f32_e32 v53, v69, v53
	v_add_f32_e32 v50, v52, v50
	v_add_f32_e32 v54, v70, v54
	v_add_f32_e32 v50, v53, v50
	v_add_f32_e32 v55, v71, v55
	v_add_f32_e32 v50, v54, v50
	v_max_f32_e32 v51, v82, v83
	v_add_f32_e32 v56, v72, v56
	v_add_f32_e32 v50, v55, v50
	v_max3_f32 v52, v84, v85, v99
	v_max3_f32 v51, v51, v98, v100
	v_add_f32_e32 v57, v73, v57
	v_add_f32_e32 v50, v56, v50
	v_max3_f32 v51, v51, v101, v86
	v_max3_f32 v52, v52, v88, v89
	v_add_f32_e32 v58, v74, v58
	v_add_f32_e32 v50, v57, v50
	v_max3_f32 v51, v51, v87, v102
	v_max3_f32 v52, v52, v104, v105
	v_add_f32_e32 v59, v75, v59
	v_add_f32_e32 v50, v58, v50
	v_max3_f32 v51, v51, v103, v90
	v_max3_f32 v52, v52, v92, v93
	v_add_f32_e32 v60, v76, v60
	v_add_f32_e32 v50, v59, v50
	v_max3_f32 v51, v51, v91, v106
	v_max3_f32 v52, v52, v108, v109
	v_add_f32_e32 v61, v77, v61
	v_add_f32_e32 v50, v60, v50
	v_max3_f32 v51, v51, v107, v94
	v_max3_f32 v52, v52, v96, v97
	v_add_f32_e32 v62, v78, v62
	v_add_f32_e32 v50, v61, v50
	v_max3_f32 v51, v51, v95, v110
	v_max3_f32 v52, v52, v112, v113
	v_add_f32_e32 v63, v79, v63
	v_add_f32_e32 v50, v62, v50
	v_max3_f32 v51, v51, v111, v52
	v_add_f32_e32 v64, v80, v64
	v_add_f32_e32 v50, v63, v50
	v_mov_b32_e32 v52, v51
	v_add_f32_e32 v65, v81, v65
	v_add_f32_e32 v50, v64, v50
	v_permlane32_swap_b32_e32 v51, v52
	v_add_f32_e32 v50, v65, v50
	v_add_f32_e32 v180, v203, v50
	v_sub_f32_e32 v50, v204, v204
	v_max_f32_e32 v51, v51, v52
	v_sub_f32_e32 v51, v51, v50
	v_cmp_lt_f32_e32 vcc, s97, v51
	v_cmp_neq_f32_e64 s[8:9], 0, v50
	s_or_b64 vcc, s[8:9], vcc
	s_cbranch_vccnz .Lat1_resc_b
	v_mov_b32_e32 v205, v204
; #define AT_STEPM(C0, C1, MC, N0, N1, MN, t_) do { \
;         AT_WRITEK((t_) + 1); AT_WRITEV(t_); \
;         __syncthreads(); \
;         AT_LOADK((t_) + 2); AT_LOADV((t_) + 1); \
;         AT_SM1(C0, C1, MC, t_, 0); MN = mref; AT_QK(N0, N1, (t_) + 1); AT_SM2(C0, C1, t_); \
;     } while (0)
; DI void attn_unit(int wv, int h, int qb, const bf16_t* QB, const bf16_t* KB, const bf16_t* VT, bf16_t* MIX, LAS unsigned char* lds) {
;     ...
;         AT_STEPM(pA0, pA1, mA, pB0, pB1, mB, t);
;         AT_STEPM(pB0, pB1, mB, pA0, pA1, mA, t + 1);
.LBB0_820:
	ds_read_b128 v[66:69], v201
	ds_read_b128 v[70:73], v201 offset:32
	v_add_u32_e32 v209, 0x8800, v179
	v_exp_f32_e32 v163, v86
	v_exp_f32_e32 v162, v87
	s_waitcnt lgkmcnt(1)
	v_mfma_f32_32x32x16_bf16 v[50:65], v[66:69], v[114:117], v[34:49]
	v_exp_f32_e32 v82, v82
	v_exp_f32_e32 v83, v83
	v_exp_f32_e32 v84, v84
	v_exp_f32_e32 v85, v85
	v_exp_f32_e32 v87, v104
	v_exp_f32_e32 v86, v105
	s_waitcnt lgkmcnt(0)
	v_mfma_f32_32x32x16_bf16 v[50:65], v[70:73], v[118:121], v[50:65]
	ds_read_b128 v[66:69], v201 offset:64
	ds_read_b128 v[70:73], v201 offset:96
	v_exp_f32_e32 v175, v102
	v_exp_f32_e32 v174, v103
	v_cvt_pk_bf16_f32 v102, v82, v83
	v_cvt_pk_bf16_f32 v103, v84, v85
	v_cvt_pk_bf16_f32 v104, v163, v162
	v_exp_f32_e32 v177, v96
	s_waitcnt lgkmcnt(1)
	v_mfma_f32_32x32x16_bf16 v[50:65], v[66:69], v[122:125], v[50:65]
	ds_read_b128 v[66:69], v201 offset:128
	v_exp_f32_e32 v176, v97
	v_exp_f32_e32 v98, v98
	v_exp_f32_e32 v99, v99
	v_exp_f32_e32 v100, v100
	v_exp_f32_e32 v101, v101
	v_add_f32_e32 v181, v98, v82
	s_waitcnt lgkmcnt(1)
	v_mfma_f32_32x32x16_bf16 v[50:65], v[70:73], v[126:129], v[50:65]
	ds_read_b128 v[166:169], v201 offset:6656
	ds_read_b128 v[170:173], v201 offset:6688
	ds_read_b128 v[182:185], v201 offset:6720
	ds_read_b128 v[186:189], v201 offset:6752
	ds_read_b128 v[70:73], v201 offset:160
	ds_read_b128 v[210:213], v201 offset:6784
	ds_read_b128 v[214:217], v201 offset:6816
	v_add_f32_e32 v203, v99, v83
	v_add_f32_e32 v181, 0, v181
	v_add_f32_e32 v228, v100, v84
	v_add_f32_e32 v181, v203, v181
	v_add_f32_e32 v229, v101, v85
	s_waitcnt lgkmcnt(7)
	v_mfma_f32_32x32x16_bf16 v[50:65], v[66:69], v[130:133], v[50:65]
	v_add_f32_e64 v218, v174, v162
	v_add_f32_e64 v219, v175, v163
	s_add_i32 s12, s12, 2
	s_add_i32 s0, s90, 2
	s_add_i32 s1, s89, 2
	s_waitcnt lgkmcnt(2)
	v_mfma_f32_32x32x16_bf16 v[50:65], v[70:73], v[134:137], v[50:65]
	s_cmp_ge_u32 s12, s29
	v_mfma_f32_32x32x16_bf16 v[66:81], v[166:169], v[114:117], v[34:49]
	v_exp_f32_e32 v167, v88
	v_exp_f32_e32 v166, v89
	v_exp_f32_e32 v169, v90
	v_exp_f32_e32 v89, v106
	v_exp_f32_e32 v168, v91
	v_exp_f32_e32 v88, v107
	v_exp_f32_e32 v91, v108
	v_mfma_f32_32x32x16_bf16 v[66:81], v[170:173], v[118:121], v[66:81]
	v_exp_f32_e32 v90, v109
	ds_read2_b64 v[106:109], v209 offset0:64 offset1:66
	v_exp_f32_e32 v171, v92
	v_exp_f32_e32 v170, v93
	v_exp_f32_e32 v93, v110
	v_exp_f32_e32 v92, v111
	v_mfma_f32_32x32x16_bf16 v[66:81], v[182:185], v[122:125], v[66:81]
	v_cvt_pk_bf16_f32 v105, v167, v166
	v_exp_f32_e32 v173, v94
	v_exp_f32_e32 v172, v95
	v_exp_f32_e32 v95, v112
	v_exp_f32_e32 v94, v113
	ds_read2_b64 v[110:113], v209 offset0:68 offset1:70
	v_add_f32_e32 v220, v86, v166
	v_add_f32_e32 v221, v87, v167
	v_mfma_f32_32x32x16_bf16 v[66:81], v[186:189], v[126:129], v[66:81]
	v_add_f32_e32 v222, v88, v168
	v_add_f32_e32 v223, v89, v169
	v_add_f32_e32 v96, v90, v170
	v_add_f32_e32 v97, v91, v171
	v_add_f32_e32 v224, v92, v172
	v_add_f32_e32 v225, v93, v173
	v_add_f32_e32 v226, v94, v176
	v_add_f32_e32 v227, v95, v177
	s_waitcnt lgkmcnt(3)
	v_mfma_f32_32x32x16_bf16 v[66:81], v[210:213], v[130:133], v[66:81]
	v_add_u32_e32 v210, 0x9800, v179
	ds_read2_b64 v[182:185], v210 offset0:96 offset1:98
	s_nop 0
	v_cvt_pk_bf16_f32 v212, v89, v88
	s_waitcnt lgkmcnt(2)
	v_mfma_f32_32x32x16_bf16 v[2:17], v[106:109], v[102:105], v[2:17]
	v_cvt_pk_bf16_f32 v106, v169, v168
	v_cvt_pk_bf16_f32 v107, v171, v170
	v_cvt_pk_bf16_f32 v108, v173, v172
	v_cvt_pk_bf16_f32 v109, v177, v176
	s_waitcnt lgkmcnt(0)
	v_mfma_f32_32x32x16_bf16 v[18:33], v[182:185], v[102:105], v[18:33]
	ds_read2_b64 v[102:105], v210 offset0:100 offset1:102
	v_cvt_pk_bf16_f32 v184, v175, v174
	v_cvt_pk_bf16_f32 v185, v87, v86
	v_cvt_pk_bf16_f32 v182, v98, v99
	v_cvt_pk_bf16_f32 v183, v100, v101
	v_mfma_f32_32x32x16_bf16 v[2:17], v[110:113], v[106:109], v[2:17]
	ds_read2_b64 v[110:113], v209 offset0:72 offset1:74
	ds_read2_b64 v[186:189], v210 offset0:104 offset1:106
	s_waitcnt lgkmcnt(2)
	v_mfma_f32_32x32x16_bf16 v[18:33], v[102:105], v[106:109], v[18:33]
	s_waitcnt lgkmcnt(1)
	v_mfma_f32_32x32x16_bf16 v[2:17], v[110:113], v[182:185], v[2:17]
	v_add_f32_e32 v110, v228, v181
	v_add_f32_e32 v110, v229, v110
	v_add_f32_e32 v110, v219, v110
	v_add_f32_e32 v110, v218, v110
	v_add_f32_e32 v110, v221, v110
	v_add_f32_e32 v110, v220, v110
	v_add_f32_e32 v110, v223, v110
	s_waitcnt lgkmcnt(0)
	v_mfma_f32_32x32x16_bf16 v[18:33], v[186:189], v[182:185], v[18:33]
	v_add_f32_e32 v110, v222, v110
	v_add_f32_e32 v97, v97, v110
	v_add_f32_e32 v96, v96, v97
	v_add_f32_e32 v96, v225, v96
	v_add_f32_e32 v96, v224, v96
	v_add_f32_e32 v96, v227, v96
	v_add_f32_e32 v96, v226, v96
	v_mfma_f32_32x32x16_bf16 v[66:81], v[214:217], v[134:137], v[66:81]
	v_add_f32_e32 v203, v180, v96
	v_cvt_pk_bf16_f32 v213, v91, v90
	v_cvt_pk_bf16_f32 v214, v93, v92
	v_cvt_pk_bf16_f32 v215, v95, v94
	ds_read2_b64 v[102:105], v209 offset0:76 offset1:78
	ds_read2_b64 v[106:109], v210 offset0:108 offset1:110
	s_waitcnt lgkmcnt(1)
	v_mfma_f32_32x32x16_bf16 v[2:17], v[102:105], v[212:215], v[2:17]
	s_waitcnt lgkmcnt(0)
	v_mfma_f32_32x32x16_bf16 v[18:33], v[106:109], v[212:215], v[18:33]
	s_cbranch_scc0 .LBB0_800
	s_add_i32 s91, s29, 4
	s_mov_b64 s[8:9], -1
	s_cmp_lt_u32 s12, s91
	v_lshlrev_b32_e32 v158, 2, v178
	s_cbranch_scc1 .LBB0_823
	v_lshlrev_b32_e32 v0, 2, v178
	s_mov_b64 s[8:9], 0

; #define AT_LOADK(t_) do { const size_t kb_ = (size_t)(t_) * 64; rk0 = *(const u32x4*)(Kh + (kb_ + kkey0) * 96 + kpart0 * 8); if (tid < 256) rk1 = *(const u32x4*)(Kh + (kb_ + kkey1) * 96 + kpart1 * 8); } while (0)
; #define AT_LOADV(t_) do { rv = *(const u32x4*)(Vh + (size_t)vdv * S + (size_t)(t_) * 64 + vpart * 8); } while (0)
; #define AT_WRITEK(t_) do { LAS unsigned char* Ks_ = lds + ((t_) & 1) * AT_KT; *(LAS u32x4*)(Ks_ + kkey0 * AT_KROW + kpart0 * 16) = rk0; if (tid < 256) *(LAS u32x4*)(Ks_ + kkey1 * AT_KROW + kpart1 * 16) = rk1; } while (0)
; DI void attn_unit(int wv, int h, int qb, const bf16_t* QB, const bf16_t* KB, const bf16_t* VT, bf16_t* MIX, LAS unsigned char* lds) {
;     ...
;     f32x16 pA0, pA1, pB0 = {}, pB1 = {}; float mA = 0.f, mB = 0.f;
;     AT_LOADK(0); AT_WRITEK(0);
;     __syncthreads();
;     AT_LOADK(1); AT_LOADV(0);
;     AT_QK(pA0, pA1, 0);
.LBB0_871:
	s_or_b64 exec, exec, s[8:9]
	v_mad_u32_u24 v3, v8, s37, 0
	v_add_u32_e32 v203, v3, v0
	ds_read_b128 v[4:7], v203
	ds_read_b128 v[12:15], v203 offset:32
	v_ashrrev_i32_e32 v20, 3, v10
	v_ashrrev_i32_e32 v21, 31, v20
	v_and_b32_e32 v0, 7, v9
	s_waitcnt lgkmcnt(1)
	v_mfma_f32_32x32x16_bf16 v[64:79], v[4:7], v[128:131], 0
	ds_read_b128 v[4:7], v203 offset:6656
	ds_read_b128 v[16:19], v203 offset:6688
	v_lshlrev_b64 v[174:175], 15, v[20:21]
	v_lshlrev_b32_e32 v168, 4, v0
	v_mov_b32_e32 v169, v1
	v_mad_i64_i32 v[176:177], s[0:1], v11, s34, 0
	v_lshlrev_b32_e32 v0, 3, v187
	s_waitcnt lgkmcnt(2)
	v_mfma_f32_32x32x16_bf16 v[64:79], v[12:15], v[132:135], v[64:79]
	s_lshl_b32 s15, s5, 2
	v_add_u32_e32 v204, 0, v0
	v_mul_lo_u32 v0, v20, s38
	s_mov_b32 s76, 0
	s_cmp_eq_u32 s5, 0
	v_mul_u32_u24_e32 v205, 0x88, v8
	v_add_u32_e32 v206, 0, v2
	s_waitcnt lgkmcnt(1)
	v_mfma_f32_32x32x16_bf16 v[80:95], v[4:7], v[128:131], 0
	ds_read_b128 v[4:7], v203 offset:64
	ds_read_b128 v[12:15], v203 offset:96
	v_add_u32_e32 v207, 0, v0
	s_waitcnt lgkmcnt(1)
	v_mfma_f32_32x32x16_bf16 v[64:79], v[4:7], v[136:139], v[64:79]
	ds_read_b128 v[4:7], v203 offset:6720
	v_mfma_f32_32x32x16_bf16 v[80:95], v[16:19], v[132:135], v[80:95]
	ds_read_b128 v[16:19], v203 offset:6752
	s_waitcnt lgkmcnt(1)
	v_mfma_f32_32x32x16_bf16 v[80:95], v[4:7], v[136:139], v[80:95]
	v_lshl_add_u64 v[4:5], s[80:81], 0, v[174:175]
	v_lshl_add_u64 v[4:5], v[4:5], 0, v[168:169]
	global_load_dwordx4 v[160:163], v[4:5], off
	ds_read_b128 v[4:7], v203 offset:128
	v_mfma_f32_32x32x16_bf16 v[64:79], v[12:15], v[140:143], v[64:79]
	s_waitcnt lgkmcnt(1)
	v_mfma_f32_32x32x16_bf16 v[80:95], v[16:19], v[140:143], v[80:95]
	ds_read_b128 v[10:13], v203 offset:6784
	ds_read_b128 v[14:17], v203 offset:160
	s_waitcnt lgkmcnt(2)
	v_mfma_f32_32x32x16_bf16 v[64:79], v[4:7], v[144:147], v[64:79]
	ds_read_b128 v[4:7], v203 offset:6816
	s_waitcnt lgkmcnt(2)
	v_mfma_f32_32x32x16_bf16 v[80:95], v[10:13], v[144:147], v[80:95]
	s_waitcnt lgkmcnt(1)
	v_mfma_f32_32x32x16_bf16 v[64:79], v[14:17], v[148:151], v[64:79]
	s_waitcnt lgkmcnt(0)
	v_mfma_f32_32x32x16_bf16 v[80:95], v[4:7], v[148:151], v[80:95]
	s_cbranch_scc1 .LBB0_895
	v_mov_b64_e32 v[2:3], s[70:71]
	v_mad_i64_i32 v[2:3], s[0:1], v186, s34, v[2:3]
	v_lshl_add_u64 v[178:179], v[172:173], 1, v[2:3]
	v_lshl_add_u64 v[2:3], s[70:71], 0, v[176:177]
	v_lshl_add_u64 v[180:181], v[170:171], 1, v[2:3]
	v_lshl_add_u64 v[2:3], s[40:41], 0, v[174:175]
	v_mov_b32_e32 v14, v1
	v_mov_b32_e32 v15, v1
	v_lshl_add_u64 v[182:183], v[2:3], 0, v[168:169]
	v_mov_b32_e32 v0, v1
	v_mov_b32_e32 v2, v1
	v_mov_b32_e32 v3, v1
	v_mov_b32_e32 v4, v1
	v_mov_b32_e32 v5, v1
	v_mov_b32_e32 v6, v1
	v_mov_b32_e32 v7, v1
	v_mov_b32_e32 v8, v1
	v_mov_b32_e32 v9, v1
	v_mov_b32_e32 v10, v1
	v_mov_b32_e32 v11, v1
	v_mov_b32_e32 v12, v1
	v_mov_b32_e32 v13, v1
	v_mov_b64_e32 v[46:47], v[14:15]
	v_mov_b64_e32 v[30:31], v[14:15]
	v_mov_b64_e32 v[62:63], v[14:15]
	v_readlane_b32 s88, v240, 15
	v_mov_b32_e32 v210, 0
	v_add_u32_e32 v169, v206, v202
	v_mov_b64_e32 v[44:45], v[12:13]
	v_mov_b64_e32 v[42:43], v[10:11]
	v_mov_b64_e32 v[40:41], v[8:9]
	v_mov_b64_e32 v[38:39], v[6:7]
	v_mov_b64_e32 v[36:37], v[4:5]
	v_mov_b64_e32 v[34:35], v[2:3]
	v_mov_b64_e32 v[32:33], v[0:1]
	v_mov_b64_e32 v[28:29], v[12:13]
	v_mov_b64_e32 v[26:27], v[10:11]
	v_mov_b64_e32 v[24:25], v[8:9]
	v_mov_b64_e32 v[22:23], v[6:7]
	v_mov_b64_e32 v[20:21], v[4:5]
	v_mov_b64_e32 v[18:19], v[2:3]
	v_mov_b64_e32 v[16:17], v[0:1]
	v_mov_b64_e32 v[60:61], v[12:13]
	v_mov_b64_e32 v[58:59], v[10:11]
	v_mov_b64_e32 v[56:57], v[8:9]
	v_mov_b64_e32 v[54:55], v[6:7]
	v_mov_b64_e32 v[52:53], v[4:5]
	v_mov_b64_e32 v[50:51], v[2:3]
	v_mov_b64_e32 v[48:49], v[0:1]
	v_mov_b32_e32 v208, 0
	v_readlane_b32 s89, v240, 16
	s_add_u32 s52, s94, 0xad71000
	s_addc_u32 s53, s95, 0
	s_add_u32 s54, s94, 0xad74000
	s_addc_u32 s55, s95, 0
	s_add_u32 s56, s94, 0xc56b000
	s_addc_u32 s57, s95, 0
	s_branch .LBB0_876
.Lat2_first:
	s_mov_b64 s[10:11], -1
	v_mov_b32_e32 v97, v96
	s_branch .Lat2_apply
.Lat2_resc:
	s_mov_b64 s[10:11], 0
	v_max_f32_e32 v97, 0, v96
.Lat2_apply:
	v_exp_f32_e64 v48, -v97
	v_add_f32_e32 v0, v0, v97
	v_add_f32_e32 v209, v210, v97
	v_pk_add_f32 v[64:65], v[64:65], v[0:1] op_sel_hi:[1,0] neg_lo:[0,1] neg_hi:[0,1]
	v_pk_add_f32 v[80:81], v[80:81], v[0:1] op_sel_hi:[1,0] neg_lo:[0,1] neg_hi:[0,1]
	v_pk_add_f32 v[66:67], v[66:67], v[0:1] op_sel_hi:[1,0] neg_lo:[0,1] neg_hi:[0,1]
	v_pk_add_f32 v[82:83], v[82:83], v[0:1] op_sel_hi:[1,0] neg_lo:[0,1] neg_hi:[0,1]
	v_pk_add_f32 v[68:69], v[68:69], v[0:1] op_sel_hi:[1,0] neg_lo:[0,1] neg_hi:[0,1]
	v_pk_add_f32 v[84:85], v[84:85], v[0:1] op_sel_hi:[1,0] neg_lo:[0,1] neg_hi:[0,1]
	v_pk_add_f32 v[70:71], v[70:71], v[0:1] op_sel_hi:[1,0] neg_lo:[0,1] neg_hi:[0,1]
	v_pk_add_f32 v[86:87], v[86:87], v[0:1] op_sel_hi:[1,0] neg_lo:[0,1] neg_hi:[0,1]
	v_pk_add_f32 v[72:73], v[72:73], v[0:1] op_sel_hi:[1,0] neg_lo:[0,1] neg_hi:[0,1]
	v_pk_add_f32 v[88:89], v[88:89], v[0:1] op_sel_hi:[1,0] neg_lo:[0,1] neg_hi:[0,1]
	v_pk_add_f32 v[74:75], v[74:75], v[0:1] op_sel_hi:[1,0] neg_lo:[0,1] neg_hi:[0,1]
	v_pk_add_f32 v[90:91], v[90:91], v[0:1] op_sel_hi:[1,0] neg_lo:[0,1] neg_hi:[0,1]
	v_pk_add_f32 v[76:77], v[76:77], v[0:1] op_sel_hi:[1,0] neg_lo:[0,1] neg_hi:[0,1]
	v_pk_add_f32 v[92:93], v[92:93], v[0:1] op_sel_hi:[1,0] neg_lo:[0,1] neg_hi:[0,1]
	v_pk_add_f32 v[78:79], v[78:79], v[0:1] op_sel_hi:[1,0] neg_lo:[0,1] neg_hi:[0,1]
	v_pk_add_f32 v[94:95], v[94:95], v[0:1] op_sel_hi:[1,0] neg_lo:[0,1] neg_hi:[0,1]
	v_cndmask_b32_e64 v0, v48, 1.0, s[10:11]
	v_xor_b32_e32 v48, 0x80000000, v209
	v_pk_mul_f32 v[46:47], v[46:47], v[0:1] op_sel_hi:[1,0]
	v_pk_mul_f32 v[44:45], v[44:45], v[0:1] op_sel_hi:[1,0]
	v_pk_mul_f32 v[42:43], v[42:43], v[0:1] op_sel_hi:[1,0]
	v_pk_mul_f32 v[40:41], v[40:41], v[0:1] op_sel_hi:[1,0]
	v_pk_mul_f32 v[38:39], v[38:39], v[0:1] op_sel_hi:[1,0]
	v_pk_mul_f32 v[36:37], v[36:37], v[0:1] op_sel_hi:[1,0]
	v_pk_mul_f32 v[34:35], v[34:35], v[0:1] op_sel_hi:[1,0]
	v_pk_mul_f32 v[32:33], v[32:33], v[0:1] op_sel_hi:[1,0]
	v_pk_mul_f32 v[30:31], v[30:31], v[0:1] op_sel_hi:[1,0]
	v_pk_mul_f32 v[28:29], v[28:29], v[0:1] op_sel_hi:[1,0]
	v_pk_mul_f32 v[26:27], v[26:27], v[0:1] op_sel_hi:[1,0]
	v_pk_mul_f32 v[24:25], v[24:25], v[0:1] op_sel_hi:[1,0]
	v_pk_mul_f32 v[22:23], v[22:23], v[0:1] op_sel_hi:[1,0]
	v_pk_mul_f32 v[20:21], v[20:21], v[0:1] op_sel_hi:[1,0]
	v_pk_mul_f32 v[18:19], v[18:19], v[0:1] op_sel_hi:[1,0]
	v_pk_mul_f32 v[16:17], v[16:17], v[0:1] op_sel_hi:[1,0]
	v_mul_f32_e32 v208, v208, v0
	v_mov_b32_e32 v49, v48
	v_mov_b32_e32 v50, v48
	v_mov_b32_e32 v51, v48
	v_mov_b32_e32 v52, v48
	v_mov_b32_e32 v53, v48
	v_mov_b32_e32 v54, v48
	v_mov_b32_e32 v55, v48
	v_mov_b32_e32 v56, v48
	v_mov_b32_e32 v57, v48
	v_mov_b32_e32 v58, v48
	v_mov_b32_e32 v59, v48
	v_mov_b32_e32 v60, v48
	v_mov_b32_e32 v61, v48
	v_mov_b32_e32 v62, v48
	v_mov_b32_e32 v63, v48
	s_branch .LBB0_889
.Lat2_resc_b:
	v_max_f32_e32 v3, v3, v3
	v_max_f32_e32 v3, 0, v3
	v_exp_f32_e64 v4, -v3
	v_add_f32_e32 v210, v209, v3
	v_add_f32_e32 v2, v2, v3
	v_xor_b32_e32 v48, 0x80000000, v210
	v_pk_add_f32 v[96:97], v[96:97], v[2:3] op_sel_hi:[1,0] neg_lo:[0,1] neg_hi:[0,1]
	v_pk_add_f32 v[112:113], v[112:113], v[2:3] op_sel_hi:[1,0] neg_lo:[0,1] neg_hi:[0,1]
	v_pk_add_f32 v[98:99], v[98:99], v[2:3] op_sel_hi:[1,0] neg_lo:[0,1] neg_hi:[0,1]
	v_pk_add_f32 v[114:115], v[114:115], v[2:3] op_sel_hi:[1,0] neg_lo:[0,1] neg_hi:[0,1]
	v_pk_add_f32 v[100:101], v[100:101], v[2:3] op_sel_hi:[1,0] neg_lo:[0,1] neg_hi:[0,1]
	v_pk_add_f32 v[116:117], v[116:117], v[2:3] op_sel_hi:[1,0] neg_lo:[0,1] neg_hi:[0,1]
	v_pk_add_f32 v[102:103], v[102:103], v[2:3] op_sel_hi:[1,0] neg_lo:[0,1] neg_hi:[0,1]
	v_pk_add_f32 v[118:119], v[118:119], v[2:3] op_sel_hi:[1,0] neg_lo:[0,1] neg_hi:[0,1]
	v_pk_add_f32 v[104:105], v[104:105], v[2:3] op_sel_hi:[1,0] neg_lo:[0,1] neg_hi:[0,1]
	v_pk_add_f32 v[120:121], v[120:121], v[2:3] op_sel_hi:[1,0] neg_lo:[0,1] neg_hi:[0,1]
	v_pk_add_f32 v[106:107], v[106:107], v[2:3] op_sel_hi:[1,0] neg_lo:[0,1] neg_hi:[0,1]
	v_pk_add_f32 v[122:123], v[122:123], v[2:3] op_sel_hi:[1,0] neg_lo:[0,1] neg_hi:[0,1]
	v_pk_add_f32 v[108:109], v[108:109], v[2:3] op_sel_hi:[1,0] neg_lo:[0,1] neg_hi:[0,1]
	v_pk_add_f32 v[124:125], v[124:125], v[2:3] op_sel_hi:[1,0] neg_lo:[0,1] neg_hi:[0,1]
	v_pk_add_f32 v[110:111], v[110:111], v[2:3] op_sel_hi:[1,0] neg_lo:[0,1] neg_hi:[0,1]
	v_pk_add_f32 v[126:127], v[126:127], v[2:3] op_sel_hi:[1,0] neg_lo:[0,1] neg_hi:[0,1]
	v_pk_mul_f32 v[46:47], v[46:47], v[4:5] op_sel_hi:[1,0]
	v_pk_mul_f32 v[44:45], v[44:45], v[4:5] op_sel_hi:[1,0]
	v_pk_mul_f32 v[42:43], v[42:43], v[4:5] op_sel_hi:[1,0]
	v_pk_mul_f32 v[40:41], v[40:41], v[4:5] op_sel_hi:[1,0]
	v_pk_mul_f32 v[38:39], v[38:39], v[4:5] op_sel_hi:[1,0]
	v_pk_mul_f32 v[36:37], v[36:37], v[4:5] op_sel_hi:[1,0]
	v_pk_mul_f32 v[34:35], v[34:35], v[4:5] op_sel_hi:[1,0]
	v_pk_mul_f32 v[32:33], v[32:33], v[4:5] op_sel_hi:[1,0]
	v_pk_mul_f32 v[30:31], v[30:31], v[4:5] op_sel_hi:[1,0]
	v_pk_mul_f32 v[28:29], v[28:29], v[4:5] op_sel_hi:[1,0]
	v_pk_mul_f32 v[26:27], v[26:27], v[4:5] op_sel_hi:[1,0]
	v_pk_mul_f32 v[24:25], v[24:25], v[4:5] op_sel_hi:[1,0]
	v_pk_mul_f32 v[22:23], v[22:23], v[4:5] op_sel_hi:[1,0]
	v_pk_mul_f32 v[20:21], v[20:21], v[4:5] op_sel_hi:[1,0]
	v_pk_mul_f32 v[18:19], v[18:19], v[4:5] op_sel_hi:[1,0]
	v_pk_mul_f32 v[16:17], v[16:17], v[4:5] op_sel_hi:[1,0]
	v_mul_f32_e32 v188, v188, v4
	v_mov_b32_e32 v49, v48
	v_mov_b32_e32 v50, v48
	v_mov_b32_e32 v51, v48
	v_mov_b32_e32 v52, v48
	v_mov_b32_e32 v53, v48
	v_mov_b32_e32 v54, v48
	v_mov_b32_e32 v55, v48
	v_mov_b32_e32 v56, v48
	v_mov_b32_e32 v57, v48
	v_mov_b32_e32 v58, v48
	v_mov_b32_e32 v59, v48
	v_mov_b32_e32 v60, v48
	v_mov_b32_e32 v61, v48
	v_mov_b32_e32 v62, v48
	v_mov_b32_e32 v63, v48
	s_branch .LBB0_875
.LBB0_873:
	s_or_b64 exec, exec, s[8:9]
	global_load_dwordx4 v[160:163], v182, s[56:57] offset:256
	v_add_f32_e32 v4, v82, v66
	v_add_u32_e32 v178, 0x6000, v178
	v_add_u32_e32 v180, 0x6000, v180
	v_add_u32_e32 v182, 0x100, v182
	v_add_f32_e32 v2, v80, v64
	v_add_f32_e32 v3, v81, v65
	v_add_f32_e32 v2, v3, v2
	v_add_f32_e32 v5, v83, v67
	v_add_f32_e32 v2, v4, v2
	v_add_f32_e32 v6, v84, v68
	v_add_f32_e32 v2, v5, v2
	v_add_f32_e32 v7, v85, v69
	v_add_f32_e32 v2, v6, v2
	v_max_f32_e32 v3, v96, v97
	v_add_f32_e32 v8, v86, v70
	v_add_f32_e32 v2, v7, v2
	v_max3_f32 v4, v98, v99, v113
	v_max3_f32 v3, v3, v112, v114
	v_add_f32_e32 v9, v87, v71
	v_add_f32_e32 v2, v8, v2
	v_max3_f32 v3, v3, v115, v100
	v_max3_f32 v4, v4, v102, v103
	v_add_f32_e32 v10, v88, v72
	v_add_f32_e32 v2, v9, v2
	v_max3_f32 v3, v3, v101, v116
	v_max3_f32 v4, v4, v118, v119
	v_add_f32_e32 v11, v89, v73
	v_add_f32_e32 v2, v10, v2
	v_max3_f32 v3, v3, v117, v104
	v_max3_f32 v4, v4, v106, v107
	v_add_f32_e32 v12, v90, v74
	v_add_f32_e32 v2, v11, v2
	v_max3_f32 v3, v3, v105, v120
	v_max3_f32 v4, v4, v122, v123
	v_add_f32_e32 v13, v91, v75
	v_add_f32_e32 v2, v12, v2
	v_max3_f32 v3, v3, v121, v108
	v_max3_f32 v4, v4, v110, v111
	v_add_f32_e32 v14, v92, v76
	v_add_f32_e32 v2, v13, v2
	v_max3_f32 v3, v3, v109, v124
	v_max3_f32 v4, v4, v126, v127
	v_add_f32_e32 v15, v93, v77
	v_add_f32_e32 v2, v14, v2
	v_max3_f32 v3, v3, v125, v4
	v_add_f32_e32 v64, v94, v78
	v_add_f32_e32 v2, v15, v2
	v_mov_b32_e32 v4, v3
	v_add_f32_e32 v65, v95, v79
	v_add_f32_e32 v2, v64, v2
	v_permlane32_swap_b32_e32 v3, v4
	v_add_f32_e32 v2, v65, v2
	v_add_f32_e32 v188, v208, v2
	v_sub_f32_e32 v2, v209, v209
	v_max_f32_e32 v3, v3, v4
	v_sub_f32_e32 v3, v3, v2
	v_cmp_lt_f32_e32 vcc, s97, v3
	v_cmp_neq_f32_e64 s[8:9], 0, v2
	s_or_b64 vcc, s[8:9], vcc
	s_cbranch_vccnz .Lat2_resc_b
	v_mov_b32_e32 v210, v209

.LBB0_876:
	s_waitcnt vmcnt(1)
	ds_write_b128 v201, v[156:159] offset:13312
	s_and_saveexec_b64 s[8:9], s[6:7]
	ds_write_b128 v169, v[152:155] offset:13312
	s_or_b64 exec, exec, s[8:9]
	v_add3_u32 v0, v207, v168, s33
	s_waitcnt vmcnt(0)
	ds_write2_b64 v0, v[160:161], v[162:163] offset1:1
	s_waitcnt lgkmcnt(0)
	s_barrier
	global_load_dwordx4 v[2:5], v180, s[52:53]
	s_and_saveexec_b64 s[8:9], s[6:7]
	s_cbranch_execz .LBB0_880
	global_load_dwordx4 v[152:155], v178, s[52:53]
.LBB0_880:
	s_or_b64 exec, exec, s[8:9]
	global_load_dwordx4 v[6:9], v182, s[56:57] offset:128
	v_max_f32_e32 v96, v64, v65
	v_max3_f32 v97, v66, v67, v81
	v_max3_f32 v96, v96, v80, v82
	v_max3_f32 v96, v96, v83, v68
	v_max3_f32 v97, v97, v70, v71
	v_max3_f32 v96, v96, v69, v84
	v_max3_f32 v97, v97, v86, v87
	v_max3_f32 v96, v96, v85, v72
	v_max3_f32 v97, v97, v74, v75
	v_max3_f32 v96, v96, v73, v88
	v_max3_f32 v97, v97, v90, v91
	v_max3_f32 v96, v96, v89, v76
	v_max3_f32 v97, v97, v78, v79
	v_max3_f32 v96, v96, v77, v92
	v_max3_f32 v97, v97, v94, v95
	v_max3_f32 v96, v96, v93, v97
	v_sub_f32_e32 v0, v210, v210
	v_mov_b32_e32 v97, v96
	s_cmp_eq_u32 s76, 0
	s_nop 0
	v_permlane32_swap_b32_e32 v96, v97
	v_max_f32_e32 v96, v96, v97
	v_sub_f32_e32 v96, v96, v0
	s_cbranch_scc1 .Lat2_first
	v_cmp_lt_f32_e32 vcc, s97, v96
	v_cmp_neq_f32_e64 s[8:9], 0, v0
	s_or_b64 vcc, s[8:9], vcc
	s_cbranch_vccnz .Lat2_resc
	v_mov_b32_e32 v209, v210
.LBB0_889:
	ds_read_b128 v[112:115], v203 offset:13312
	ds_read_b128 v[116:119], v203 offset:13344
	v_add_u32_e32 v0, v204, v205
	v_add_u32_e32 v184, 0x6800, v0
	v_exp_f32_e32 v64, v64
	s_waitcnt lgkmcnt(1)
	v_mfma_f32_32x32x16_bf16 v[96:111], v[112:115], v[128:131], v[48:63]
	v_exp_f32_e32 v65, v65
	v_exp_f32_e32 v66, v66
	v_exp_f32_e32 v67, v67
	v_exp_f32_e32 v68, v68
	v_exp_f32_e32 v69, v69
	v_exp_f32_e32 v70, v70
	v_exp_f32_e32 v71, v71
	s_waitcnt lgkmcnt(0)
	v_mfma_f32_32x32x16_bf16 v[96:111], v[116:119], v[132:135], v[96:111]
	ds_read_b128 v[112:115], v203 offset:13376
	ds_read_b128 v[116:119], v203 offset:13408
	v_add_u32_e32 v185, 0x7800, v0
	v_exp_f32_e32 v72, v72
	v_exp_f32_e32 v73, v73
	v_exp_f32_e32 v74, v74
	v_exp_f32_e32 v75, v75
	v_exp_f32_e32 v76, v76
	s_waitcnt lgkmcnt(1)
	v_mfma_f32_32x32x16_bf16 v[96:111], v[112:115], v[136:139], v[96:111]
	v_exp_f32_e32 v77, v77
	v_exp_f32_e32 v78, v78
	v_exp_f32_e32 v79, v79
	v_exp_f32_e32 v80, v80
	v_exp_f32_e32 v81, v81
	v_exp_f32_e32 v82, v82
	v_exp_f32_e32 v83, v83
	s_waitcnt lgkmcnt(0)
	v_mfma_f32_32x32x16_bf16 v[96:111], v[116:119], v[140:143], v[96:111]
	ds_read_b128 v[112:115], v203 offset:13440
	ds_read_b128 v[116:119], v203 offset:13472
	ds_read_b128 v[156:159], v203 offset:19968
	ds_read_b128 v[160:163], v203 offset:20000
	v_exp_f32_e32 v84, v84
	v_exp_f32_e32 v85, v85
	v_exp_f32_e32 v86, v86
	v_exp_f32_e32 v87, v87
	v_exp_f32_e32 v88, v88
	s_waitcnt lgkmcnt(3)
	v_mfma_f32_32x32x16_bf16 v[96:111], v[112:115], v[144:147], v[96:111]
	v_exp_f32_e32 v89, v89
	v_exp_f32_e32 v90, v90
	v_exp_f32_e32 v91, v91
	v_exp_f32_e32 v92, v92
	v_exp_f32_e32 v93, v93
	v_exp_f32_e32 v94, v94
	v_exp_f32_e32 v95, v95
	s_waitcnt lgkmcnt(2)
	v_mfma_f32_32x32x16_bf16 v[96:111], v[116:119], v[148:151], v[96:111]
	s_waitcnt lgkmcnt(1)
	v_mfma_f32_32x32x16_bf16 v[112:127], v[156:159], v[128:131], v[48:63]
	s_waitcnt lgkmcnt(0)
	v_mfma_f32_32x32x16_bf16 v[112:127], v[160:163], v[132:135], v[112:127]
	ds_read_b128 v[156:159], v203 offset:20032
	ds_read_b128 v[160:163], v203 offset:20064
	s_waitcnt lgkmcnt(1)
	v_mfma_f32_32x32x16_bf16 v[112:127], v[156:159], v[136:139], v[112:127]
	s_waitcnt lgkmcnt(0)
	v_mfma_f32_32x32x16_bf16 v[112:127], v[160:163], v[140:143], v[112:127]
	ds_read_b128 v[156:159], v203 offset:20096
	ds_read_b128 v[160:163], v203 offset:20128
	ds_read2_b64 v[188:191], v184 offset0:4 offset1:6
	s_waitcnt lgkmcnt(2)
	v_mfma_f32_32x32x16_bf16 v[112:127], v[156:159], v[144:147], v[112:127]
	ds_read2_b64 v[156:159], v184 offset1:2
	s_waitcnt lgkmcnt(2)
	v_mfma_f32_32x32x16_bf16 v[112:127], v[160:163], v[148:151], v[112:127]
	v_cvt_pk_bf16_f32 v160, v64, v65
	v_cvt_pk_bf16_f32 v161, v66, v67
	v_cvt_pk_bf16_f32 v162, v68, v69
	v_cvt_pk_bf16_f32 v163, v70, v71
	s_waitcnt lgkmcnt(0)
	s_nop 0
	v_mfma_f32_32x32x16_bf16 v[32:47], v[156:159], v[160:163], v[32:47]
	ds_read2_b64 v[156:159], v185 offset0:32 offset1:34
	s_waitcnt lgkmcnt(0)
	v_mfma_f32_32x32x16_bf16 v[16:31], v[156:159], v[160:163], v[16:31]
	ds_read2_b64 v[160:163], v185 offset0:36 offset1:38
	v_cvt_pk_bf16_f32 v156, v72, v73
	v_cvt_pk_bf16_f32 v157, v74, v75
	v_cvt_pk_bf16_f32 v158, v76, v77
	v_cvt_pk_bf16_f32 v159, v78, v79
	s_nop 1
	v_mfma_f32_32x32x16_bf16 v[32:47], v[188:191], v[156:159], v[32:47]
	ds_read2_b64 v[188:191], v184 offset0:8 offset1:10
	s_waitcnt lgkmcnt(1)
	v_mfma_f32_32x32x16_bf16 v[16:31], v[160:163], v[156:159], v[16:31]
	ds_read2_b64 v[160:163], v185 offset0:40 offset1:42
	v_cvt_pk_bf16_f32 v156, v80, v81
	v_cvt_pk_bf16_f32 v157, v82, v83
	v_cvt_pk_bf16_f32 v158, v84, v85
	v_cvt_pk_bf16_f32 v159, v86, v87
	s_waitcnt lgkmcnt(1)
	s_nop 0
	v_mfma_f32_32x32x16_bf16 v[32:47], v[188:191], v[156:159], v[32:47]
	ds_read2_b64 v[188:191], v184 offset0:12 offset1:14
	s_waitcnt lgkmcnt(1)
	v_mfma_f32_32x32x16_bf16 v[16:31], v[160:163], v[156:159], v[16:31]
	ds_read2_b64 v[160:163], v185 offset0:44 offset1:46
	v_cvt_pk_bf16_f32 v156, v88, v89
	v_cvt_pk_bf16_f32 v157, v90, v91
	v_cvt_pk_bf16_f32 v158, v92, v93
	v_cvt_pk_bf16_f32 v159, v94, v95
	s_waitcnt vmcnt(1)
	ds_write_b128 v201, v[2:5]
	s_waitcnt lgkmcnt(2)
	v_mfma_f32_32x32x16_bf16 v[32:47], v[188:191], v[156:159], v[32:47]
	s_waitcnt lgkmcnt(1)
	v_mfma_f32_32x32x16_bf16 v[16:31], v[160:163], v[156:159], v[16:31]
	s_and_saveexec_b64 s[8:9], s[6:7]
	ds_write_b128 v169, v[152:155]
	s_or_b64 exec, exec, s[8:9]
	v_add3_u32 v2, v207, v168, s4
	s_waitcnt vmcnt(0)
	ds_write2_b64 v2, v[6:7], v[8:9] offset1:1
	s_waitcnt lgkmcnt(0)
	s_barrier
	global_load_dwordx4 v[156:159], v180, s[54:55]
	s_and_saveexec_b64 s[8:9], s[6:7]
	s_cbranch_execz .LBB0_873
	global_load_dwordx4 v[152:155], v178, s[54:55]
	s_branch .LBB0_873
